# resid S-path stream loads/stores in lane-adjacent layout (ds_bpermute) on top of v10
# speedup vs baseline: 1.0843x; 1.0107x over previous
; #define PG8_STAGE(bufoff, gbase, voff) do { _Pragma("unroll") for (int _i = 0; _i < 2; ++_i) \
;     __builtin_amdgcn_global_load_lds((const unsigned*)((const char*)(gbase) + (voff)[_i]), (PG8_LAS unsigned*)(lds + (bufoff) + ldsw + _i * 8192), 16, 0, 0); } while (0)
; #define PG8_LDA(dst, b, h) do { _Pragma("unroll") for (int m = 0; m < 4; ++m) _Pragma("unroll") for (int k = 0; k < 2; ++k) dst[m][k] = *(const PG8_LAS bf16x8*)(lds + PG8_SA(b, h) + aoff + m * 2048 + k * 1024); } while (0)
; #define PG8_LDB(dst, b, h) do { _Pragma("unroll") for (int n = 0; n < 2; ++n) _Pragma("unroll") for (int k = 0; k < 2; ++k) dst[n][k] = *(const PG8_LAS bf16x8*)(lds + PG8_SB(b, h) + boff + n * 2048 + k * 1024); } while (0)
; #define PG8_MMA(ai, bj, At, Bt) do { __builtin_amdgcn_s_setprio(1); _Pragma("unroll") for (int m = 0; m < 4; ++m) _Pragma("unroll") for (int n = 0; n < 2; ++n) _Pragma("unroll") for (int k = 0; k < 2; ++k) \
;     acc[ai][bj][m][n] = __builtin_amdgcn_mfma_f32_16x16x32_bf16(Bt[n][k], At[m][k], acc[ai][bj][m][n], 0, 0, 0); __builtin_amdgcn_s_setprio(0); } while (0)
; #define PG8_WAIT_L(n) asm volatile("s_waitcnt lgkmcnt(" #n ")" ::: "memory")
; #define PG8_BAR __builtin_amdgcn_s_barrier()
; #define PG8_SCHED __builtin_amdgcn_sched_barrier(0)
; template <class Epi>
; DI void gemm_phase(PG8_LAS unsigned char* lds, const Gemm g, const StaticOrder& S, const Epi& E) {
;     ...
;     const bool has_next = S.next(ui + 1, nxt);
;     const char* nA = has_next ? (const char*)g.A + (size_t)nxt.pm * tstepA : cA; const char* nB = has_next ? (const char*)g.Bt + (size_t)nxt.pn * tstepB : cB;
;     for (int t = 0; t < nt; t += 2) {
;       const bool last = (t == nt - 2);
;       const char* a1 = cA + (size_t)(t + 1) * kstep;
;       const char* a2 = last ? nA : cA + (size_t)(t + 2) * kstep; const char* b2 = last ? nB : cB + (size_t)(t + 2) * kstep;
;       const char* a3 = a2 + kstep; const char* b3 = b2 + kstep;
;       PG8_LDB(B0, 0, 0); PG8_SCHED; PG8_LDA(At, 0, 0); PG8_STAGE(PG8_SA(1, 1), a1 + hstepA, voffA);
;       PG8_WAIT_L(8); PG8_BAR; PG8_WAIT_L(0); PG8_MMA(0, 0, At, B0); PG8_BAR; PG8_SCHED;
;       PG8_LDB(B1, 0, 1); PG8_STAGE(PG8_SB(0, 0), b2, voffB);
;       PG8_BAR; PG8_WAIT_L(0); PG8_MMA(0, 1, At, B1); PG8_BAR;
;       PG8_LDA(At, 0, 1); PG8_STAGE(PG8_SA(0, 0), a2, voffA);
;       PG8_BAR; PG8_WAIT_L(0); PG8_MMA(1, 0, At, B0); PG8_BAR; PG8_SCHED;
.LBB0_835:
	s_add_i32 s81, s56, 2
	s_add_u32 s58, s44, 0x80
	s_addc_u32 s57, s45, 0
	s_add_i32 s82, 0, 0x10000
	v_add_u32_e32 v160, s82, v223
	ds_read_b128 v[130:133], v160
	ds_read_b128 v[152:155], v160 offset:1024
	ds_read_b128 v[156:159], v160 offset:2048
	ds_read_b128 v[160:163], v160 offset:3072
	s_cmp_eq_u32 s75, s56
	s_cselect_b32 s56, s0, s58
	s_cselect_b32 s57, s1, s57
	s_cselect_b32 s59, s55, s80
	s_cselect_b32 s58, s54, s79
	v_lshl_add_u64 v[196:197], s[44:45], 0, v[148:149]
	s_add_i32 m0, s66, 0xc000
	ds_read_b128 v[164:167], v225
	ds_read_b128 v[168:171], v225 offset:1024
	ds_read_b128 v[172:175], v225 offset:2048
	ds_read_b128 v[176:179], v225 offset:3072
	ds_read_b128 v[180:183], v225 offset:4096
	ds_read_b128 v[184:187], v225 offset:5120
	ds_read_b128 v[188:191], v225 offset:6144
	ds_read_b128 v[192:195], v225 offset:7168
	global_load_lds_dwordx4 v[196:197], off
	v_lshl_add_u64 v[196:197], s[44:45], 0, v[150:151]
	s_add_i32 m0, s66, 0xe000
	s_nop 0
	global_load_lds_dwordx4 v[196:197], off
	s_waitcnt lgkmcnt(8)
	s_barrier
	s_waitcnt lgkmcnt(0)
	s_setprio 1
	s_waitcnt lgkmcnt(0)
	v_mfma_f32_16x16x32_bf16 v[126:129], v[130:133], v[164:167], v[126:129]
	v_mfma_f32_16x16x32_bf16 v[122:125], v[156:159], v[164:167], v[122:125]
	v_mfma_f32_16x16x32_bf16 v[110:113], v[130:133], v[172:175], v[110:113]
	v_mfma_f32_16x16x32_bf16 v[106:109], v[156:159], v[172:175], v[106:109]
	v_mfma_f32_16x16x32_bf16 v[94:97], v[130:133], v[180:183], v[94:97]
	v_mfma_f32_16x16x32_bf16 v[90:93], v[156:159], v[180:183], v[90:93]
	v_mfma_f32_16x16x32_bf16 v[78:81], v[130:133], v[188:191], v[78:81]
	v_mfma_f32_16x16x32_bf16 v[74:77], v[156:159], v[188:191], v[74:77]
	v_mfma_f32_16x16x32_bf16 v[126:129], v[152:155], v[168:171], v[126:129]
	v_mfma_f32_16x16x32_bf16 v[122:125], v[160:163], v[168:171], v[122:125]
	v_mfma_f32_16x16x32_bf16 v[110:113], v[152:155], v[176:179], v[110:113]
	v_mfma_f32_16x16x32_bf16 v[106:109], v[160:163], v[176:179], v[106:109]
	v_mfma_f32_16x16x32_bf16 v[94:97], v[152:155], v[184:187], v[94:97]
	v_mfma_f32_16x16x32_bf16 v[90:93], v[160:163], v[184:187], v[90:93]
	v_mfma_f32_16x16x32_bf16 v[78:81], v[152:155], v[192:195], v[78:81]
	v_mfma_f32_16x16x32_bf16 v[74:77], v[160:163], v[192:195], v[74:77]
	s_setprio 0
	s_barrier
	s_add_i32 s83, 0, 0x14000
	s_add_i32 s82, s82, s65
	v_add_u32_e32 v234, s83, v223
	v_lshl_add_u64 v[238:239], s[58:59], 0, v[0:1]
	s_mov_b32 m0, s82
	ds_read_b128 v[196:199], v234
	ds_read_b128 v[226:229], v234 offset:1024
	ds_read_b128 v[230:233], v234 offset:2048
	ds_read_b128 v[234:237], v234 offset:3072
	global_load_lds_dwordx4 v[238:239], off
	v_lshl_add_u64 v[240:241], s[58:59], 0, v[142:143]
	s_add_i32 m0, s82, 0x2000
	s_nop 0
	global_load_lds_dwordx4 v[240:241], off
	s_barrier
	s_waitcnt lgkmcnt(0)
	s_setprio 1
	s_waitcnt lgkmcnt(0)
	v_mfma_f32_16x16x32_bf16 v[118:121], v[196:199], v[164:167], v[118:121]
	v_mfma_f32_16x16x32_bf16 v[114:117], v[230:233], v[164:167], v[114:117]
	v_mfma_f32_16x16x32_bf16 v[102:105], v[196:199], v[172:175], v[102:105]
	v_mfma_f32_16x16x32_bf16 v[98:101], v[230:233], v[172:175], v[98:101]
	v_mfma_f32_16x16x32_bf16 v[86:89], v[196:199], v[180:183], v[86:89]
	v_mfma_f32_16x16x32_bf16 v[82:85], v[230:233], v[180:183], v[82:85]
	v_mfma_f32_16x16x32_bf16 v[70:73], v[196:199], v[188:191], v[70:73]
	v_mfma_f32_16x16x32_bf16 v[66:69], v[230:233], v[188:191], v[66:69]
	v_mfma_f32_16x16x32_bf16 v[118:121], v[226:229], v[168:171], v[118:121]
	v_mfma_f32_16x16x32_bf16 v[114:117], v[234:237], v[168:171], v[114:117]
	v_mfma_f32_16x16x32_bf16 v[102:105], v[226:229], v[176:179], v[102:105]
	v_mfma_f32_16x16x32_bf16 v[98:101], v[234:237], v[176:179], v[98:101]
	v_mfma_f32_16x16x32_bf16 v[86:89], v[226:229], v[184:187], v[86:89]
	v_mfma_f32_16x16x32_bf16 v[82:85], v[234:237], v[184:187], v[82:85]
	v_mfma_f32_16x16x32_bf16 v[70:73], v[226:229], v[192:195], v[70:73]
	v_mfma_f32_16x16x32_bf16 v[66:69], v[234:237], v[192:195], v[66:69]
	s_setprio 0
	s_mov_b32 m0, s66
	v_lshl_add_u64 v[242:243], s[56:57], 0, v[146:147]
	s_barrier
	ds_read_b128 v[164:167], v225 offset:16384
	ds_read_b128 v[168:171], v225 offset:17408
	ds_read_b128 v[172:175], v225 offset:18432
	ds_read_b128 v[176:179], v225 offset:19456
	ds_read_b128 v[180:183], v225 offset:20480
	ds_read_b128 v[184:187], v225 offset:21504
	ds_read_b128 v[188:191], v225 offset:22528
	ds_read_b128 v[192:195], v225 offset:23552
	global_load_lds_dwordx4 v[242:243], off
	v_lshl_add_u64 v[244:245], s[56:57], 0, v[144:145]
	s_mov_b32 m0, s67
	s_nop 0
	global_load_lds_dwordx4 v[244:245], off
	s_barrier
	s_waitcnt lgkmcnt(0)
	s_setprio 1
	s_waitcnt lgkmcnt(0)
	v_mfma_f32_16x16x32_bf16 v[62:65], v[130:133], v[164:167], v[62:65]
	v_mfma_f32_16x16x32_bf16 v[58:61], v[156:159], v[164:167], v[58:61]
	v_mfma_f32_16x16x32_bf16 v[46:49], v[130:133], v[172:175], v[46:49]
	v_mfma_f32_16x16x32_bf16 v[42:45], v[156:159], v[172:175], v[42:45]
	v_mfma_f32_16x16x32_bf16 v[30:33], v[130:133], v[180:183], v[30:33]
	v_mfma_f32_16x16x32_bf16 v[26:29], v[156:159], v[180:183], v[26:29]
	v_mfma_f32_16x16x32_bf16 v[14:17], v[130:133], v[188:191], v[14:17]
	v_mfma_f32_16x16x32_bf16 v[10:13], v[156:159], v[188:191], v[10:13]
	v_mfma_f32_16x16x32_bf16 v[62:65], v[152:155], v[168:171], v[62:65]
	v_mfma_f32_16x16x32_bf16 v[58:61], v[160:163], v[168:171], v[58:61]
	v_mfma_f32_16x16x32_bf16 v[46:49], v[152:155], v[176:179], v[46:49]
	v_mfma_f32_16x16x32_bf16 v[42:45], v[160:163], v[176:179], v[42:45]
	v_mfma_f32_16x16x32_bf16 v[30:33], v[152:155], v[184:187], v[30:33]
	v_mfma_f32_16x16x32_bf16 v[26:29], v[160:163], v[184:187], v[26:29]
	v_mfma_f32_16x16x32_bf16 v[14:17], v[152:155], v[192:195], v[14:17]
	v_mfma_f32_16x16x32_bf16 v[10:13], v[160:163], v[192:195], v[10:13]
	s_setprio 0
	s_barrier
; #define PG8_STAGE(bufoff, gbase, voff) do { _Pragma("unroll") for (int _i = 0; _i < 2; ++_i) \
;     __builtin_amdgcn_global_load_lds((const unsigned*)((const char*)(gbase) + (voff)[_i]), (PG8_LAS unsigned*)(lds + (bufoff) + ldsw + _i * 8192), 16, 0, 0); } while (0)
; #define PG8_LDA(dst, b, h) do { _Pragma("unroll") for (int m = 0; m < 4; ++m) _Pragma("unroll") for (int k = 0; k < 2; ++k) dst[m][k] = *(const PG8_LAS bf16x8*)(lds + PG8_SA(b, h) + aoff + m * 2048 + k * 1024); } while (0)
; #define PG8_LDB(dst, b, h) do { _Pragma("unroll") for (int n = 0; n < 2; ++n) _Pragma("unroll") for (int k = 0; k < 2; ++k) dst[n][k] = *(const PG8_LAS bf16x8*)(lds + PG8_SB(b, h) + boff + n * 2048 + k * 1024); } while (0)
; #define PG8_MMA(ai, bj, At, Bt) do { __builtin_amdgcn_s_setprio(1); _Pragma("unroll") for (int m = 0; m < 4; ++m) _Pragma("unroll") for (int n = 0; n < 2; ++n) _Pragma("unroll") for (int k = 0; k < 2; ++k) \
;     acc[ai][bj][m][n] = __builtin_amdgcn_mfma_f32_16x16x32_bf16(Bt[n][k], At[m][k], acc[ai][bj][m][n], 0, 0, 0); __builtin_amdgcn_s_setprio(0); } while (0)
; #define PG8_WAIT_V(n) asm volatile("s_waitcnt vmcnt(" #n ")" ::: "memory")
; #define PG8_WAIT_L(n) asm volatile("s_waitcnt lgkmcnt(" #n ")" ::: "memory")
; #define PG8_BAR __builtin_amdgcn_s_barrier()
; #define PG8_SCHED __builtin_amdgcn_sched_barrier(0)
; template <class Epi>
; DI void gemm_phase(PG8_LAS unsigned char* lds, const Gemm g, const StaticOrder& S, const Epi& E) {
;     ...
;       PG8_STAGE(PG8_SB(0, 1), b2 + hstepB, voffB);
;       PG8_WAIT_V(6); PG8_BAR; PG8_MMA(1, 1, At, B1); PG8_BAR;
;       PG8_LDB(B0, 1, 0); PG8_SCHED; PG8_LDA(At, 1, 0); PG8_STAGE(PG8_SA(0, 1), a2 + hstepA, voffA);
;       PG8_WAIT_L(8); PG8_BAR; PG8_WAIT_L(0); PG8_MMA(0, 0, At, B0); PG8_BAR; PG8_SCHED;
;       PG8_LDB(B1, 1, 1); PG8_STAGE(PG8_SB(1, 0), b3, voffB);
;       PG8_BAR; PG8_WAIT_L(0); PG8_MMA(0, 1, At, B1); PG8_BAR;
;       PG8_LDA(At, 1, 1); PG8_STAGE(PG8_SA(1, 0), a3, voffA);
;       PG8_BAR; PG8_WAIT_L(0); PG8_MMA(1, 0, At, B0); PG8_BAR; PG8_SCHED;
	s_add_u32 s58, s58, s62
	s_addc_u32 s59, s59, 0
	s_add_i32 s82, s83, s65
	v_lshl_add_u64 v[246:247], s[58:59], 0, v[0:1]
	s_mov_b32 m0, s82
	v_lshl_add_u64 v[248:249], s[58:59], 0, v[142:143]
	global_load_lds_dwordx4 v[246:247], off
	s_add_i32 m0, s82, 0x2000
	s_nop 0
	global_load_lds_dwordx4 v[248:249], off
	s_waitcnt vmcnt(6)
	s_barrier
	s_setprio 1
	v_mfma_f32_16x16x32_bf16 v[54:57], v[196:199], v[164:167], v[54:57]
	v_mfma_f32_16x16x32_bf16 v[50:53], v[230:233], v[164:167], v[50:53]
	v_mfma_f32_16x16x32_bf16 v[38:41], v[196:199], v[172:175], v[38:41]
	v_mfma_f32_16x16x32_bf16 v[34:37], v[230:233], v[172:175], v[34:37]
	v_mfma_f32_16x16x32_bf16 v[22:25], v[196:199], v[180:183], v[22:25]
	v_mfma_f32_16x16x32_bf16 v[18:21], v[230:233], v[180:183], v[18:21]
	v_mfma_f32_16x16x32_bf16 v[6:9], v[196:199], v[188:191], v[6:9]
	v_mfma_f32_16x16x32_bf16 v[2:5], v[230:233], v[188:191], v[2:5]
	v_mfma_f32_16x16x32_bf16 v[54:57], v[226:229], v[168:171], v[54:57]
	v_mfma_f32_16x16x32_bf16 v[50:53], v[234:237], v[168:171], v[50:53]
	v_mfma_f32_16x16x32_bf16 v[38:41], v[226:229], v[176:179], v[38:41]
	v_mfma_f32_16x16x32_bf16 v[34:37], v[234:237], v[176:179], v[34:37]
	v_mfma_f32_16x16x32_bf16 v[22:25], v[226:229], v[184:187], v[22:25]
	v_mfma_f32_16x16x32_bf16 v[18:21], v[234:237], v[184:187], v[18:21]
	v_mfma_f32_16x16x32_bf16 v[6:9], v[226:229], v[192:195], v[6:9]
	v_mfma_f32_16x16x32_bf16 v[2:5], v[234:237], v[192:195], v[2:5]
	s_setprio 0
	s_add_i32 s58, 0, 0x18000
	v_add_u32_e32 v160, s58, v223
	s_barrier
	ds_read_b128 v[130:133], v160
	ds_read_b128 v[152:155], v160 offset:1024
	ds_read_b128 v[156:159], v160 offset:2048
	ds_read_b128 v[160:163], v160 offset:3072
	s_add_u32 s56, s56, s50
	s_addc_u32 s57, s57, 0
	s_mov_b32 m0, s68
	v_lshl_add_u64 v[196:197], s[56:57], 0, v[146:147]
	ds_read_b128 v[164:167], v225 offset:32768
	ds_read_b128 v[168:171], v225 offset:33792
	ds_read_b128 v[172:175], v225 offset:34816
	ds_read_b128 v[176:179], v225 offset:35840
	ds_read_b128 v[180:183], v225 offset:36864
	ds_read_b128 v[184:187], v225 offset:37888
	ds_read_b128 v[188:191], v225 offset:38912
	ds_read_b128 v[192:195], v225 offset:39936
	global_load_lds_dwordx4 v[196:197], off
	v_lshl_add_u64 v[196:197], s[56:57], 0, v[144:145]
	s_mov_b32 m0, s69
	s_nop 0
	global_load_lds_dwordx4 v[196:197], off
	s_waitcnt lgkmcnt(8)
	s_barrier
	s_waitcnt lgkmcnt(0)
	s_setprio 1
	s_waitcnt lgkmcnt(0)
	v_mfma_f32_16x16x32_bf16 v[126:129], v[130:133], v[164:167], v[126:129]
	v_mfma_f32_16x16x32_bf16 v[122:125], v[156:159], v[164:167], v[122:125]
	v_mfma_f32_16x16x32_bf16 v[110:113], v[130:133], v[172:175], v[110:113]
	v_mfma_f32_16x16x32_bf16 v[106:109], v[156:159], v[172:175], v[106:109]
	v_mfma_f32_16x16x32_bf16 v[94:97], v[130:133], v[180:183], v[94:97]
	v_mfma_f32_16x16x32_bf16 v[90:93], v[156:159], v[180:183], v[90:93]
	v_mfma_f32_16x16x32_bf16 v[78:81], v[130:133], v[188:191], v[78:81]
	v_mfma_f32_16x16x32_bf16 v[74:77], v[156:159], v[188:191], v[74:77]
	v_mfma_f32_16x16x32_bf16 v[126:129], v[152:155], v[168:171], v[126:129]
	v_mfma_f32_16x16x32_bf16 v[122:125], v[160:163], v[168:171], v[122:125]
	v_mfma_f32_16x16x32_bf16 v[110:113], v[152:155], v[176:179], v[110:113]
	v_mfma_f32_16x16x32_bf16 v[106:109], v[160:163], v[176:179], v[106:109]
	v_mfma_f32_16x16x32_bf16 v[94:97], v[152:155], v[184:187], v[94:97]
	v_mfma_f32_16x16x32_bf16 v[90:93], v[160:163], v[184:187], v[90:93]
	v_mfma_f32_16x16x32_bf16 v[78:81], v[152:155], v[192:195], v[78:81]
	v_mfma_f32_16x16x32_bf16 v[74:77], v[160:163], v[192:195], v[74:77]
	s_setprio 0
	s_barrier
	s_add_i32 s56, 0, 0x1c000
	s_add_i32 s57, s58, s65
	v_add_u32_e32 v234, s56, v223
	v_lshl_add_u64 v[238:239], v[238:239], 0, s[86:87]
	s_mov_b32 m0, s57
	ds_read_b128 v[196:199], v234
	ds_read_b128 v[226:229], v234 offset:1024
	ds_read_b128 v[230:233], v234 offset:2048
	ds_read_b128 v[234:237], v234 offset:3072
	global_load_lds_dwordx4 v[238:239], off
	v_lshl_add_u64 v[238:239], v[240:241], 0, s[86:87]
	s_add_i32 m0, s57, 0x2000
	s_nop 0
	global_load_lds_dwordx4 v[238:239], off
	s_barrier
	s_waitcnt lgkmcnt(0)
	s_setprio 1
	s_waitcnt lgkmcnt(0)
	v_mfma_f32_16x16x32_bf16 v[118:121], v[196:199], v[164:167], v[118:121]
	v_mfma_f32_16x16x32_bf16 v[114:117], v[230:233], v[164:167], v[114:117]
	v_mfma_f32_16x16x32_bf16 v[102:105], v[196:199], v[172:175], v[102:105]
	v_mfma_f32_16x16x32_bf16 v[98:101], v[230:233], v[172:175], v[98:101]
	v_mfma_f32_16x16x32_bf16 v[86:89], v[196:199], v[180:183], v[86:89]
	v_mfma_f32_16x16x32_bf16 v[82:85], v[230:233], v[180:183], v[82:85]
	v_mfma_f32_16x16x32_bf16 v[70:73], v[196:199], v[188:191], v[70:73]
	v_mfma_f32_16x16x32_bf16 v[66:69], v[230:233], v[188:191], v[66:69]
	v_mfma_f32_16x16x32_bf16 v[118:121], v[226:229], v[168:171], v[118:121]
	v_mfma_f32_16x16x32_bf16 v[114:117], v[234:237], v[168:171], v[114:117]
	v_mfma_f32_16x16x32_bf16 v[102:105], v[226:229], v[176:179], v[102:105]
	v_mfma_f32_16x16x32_bf16 v[98:101], v[234:237], v[176:179], v[98:101]
	v_mfma_f32_16x16x32_bf16 v[86:89], v[226:229], v[184:187], v[86:89]
	v_mfma_f32_16x16x32_bf16 v[82:85], v[234:237], v[184:187], v[82:85]
	v_mfma_f32_16x16x32_bf16 v[70:73], v[226:229], v[192:195], v[70:73]
	v_mfma_f32_16x16x32_bf16 v[66:69], v[234:237], v[192:195], v[66:69]
	s_setprio 0
	s_mov_b32 m0, s72
	v_lshl_add_u64 v[238:239], v[242:243], 0, s[86:87]
	s_barrier
	ds_read_b128 v[164:167], v225 offset:49152
	ds_read_b128 v[168:171], v225 offset:50176
	ds_read_b128 v[172:175], v225 offset:51200
	ds_read_b128 v[176:179], v225 offset:52224
	ds_read_b128 v[180:183], v225 offset:53248
	ds_read_b128 v[184:187], v225 offset:54272
	ds_read_b128 v[188:191], v225 offset:55296
	ds_read_b128 v[192:195], v225 offset:56320
	global_load_lds_dwordx4 v[238:239], off
	v_lshl_add_u64 v[238:239], v[244:245], 0, s[86:87]
	s_mov_b32 m0, s73
	s_nop 0
	global_load_lds_dwordx4 v[238:239], off
	s_barrier
; #define PG8_LAS __attribute__((address_space(3)))
; #define PG8_STAGE(bufoff, gbase, voff) do { _Pragma("unroll") for (int _i = 0; _i < 2; ++_i) \
;     __builtin_amdgcn_global_load_lds((const unsigned*)((const char*)(gbase) + (voff)[_i]), (PG8_LAS unsigned*)(lds + (bufoff) + ldsw + _i * 8192), 16, 0, 0); } while (0)
; #define PG8_MMA(ai, bj, At, Bt) do { __builtin_amdgcn_s_setprio(1); _Pragma("unroll") for (int m = 0; m < 4; ++m) _Pragma("unroll") for (int n = 0; n < 2; ++n) _Pragma("unroll") for (int k = 0; k < 2; ++k) \
;     acc[ai][bj][m][n] = __builtin_amdgcn_mfma_f32_16x16x32_bf16(Bt[n][k], At[m][k], acc[ai][bj][m][n], 0, 0, 0); __builtin_amdgcn_s_setprio(0); } while (0)
; #define PG8_WAIT_V(n) asm volatile("s_waitcnt vmcnt(" #n ")" ::: "memory")
; #define PG8_BAR __builtin_amdgcn_s_barrier()
;   DI void operator()(const f32x4 (&acc)[2][2][4][2], const Unit& u, int wr, int wc, int fr, int fq, const PG8_LAS float* sR) const {
;     const int row0 = u.pm * BM + wr * 64 + fr, col0 = u.pn * BM + wc * 32 + 4 * fq;
; #pragma unroll
;     for (int ai = 0; ai < 2; ++ai) {
;       u32x2 sv[4][2][2];
;       if (X0 == nullptr) {
; #pragma unroll
;         for (int m = 0; m < 4; ++m)
; #pragma unroll
;           for (int bj = 0; bj < 2; ++bj)
; #pragma unroll
;             for (int n = 0; n < 2; ++n) sv[m][bj][n] = *(const u32x2*)(S + (size_t)(row0 + ai * HALF + m * 16) * 1024 + col0 + bj * HALF + n * 16);
; template <class Epi>
; DI void gemm_phase(PG8_LAS unsigned char* lds, const Gemm g, const StaticOrder& S, const Epi& E) {
;     ...
;       PG8_STAGE(PG8_SB(1, 1), b3 + hstepB, voffB);
;       PG8_WAIT_V(6); PG8_BAR; PG8_MMA(1, 1, At, B1); PG8_BAR;
;     }
;     const PG8_LAS float* sR = (const PG8_LAS float*)(lds + 131072) + ui * 256 + wr * 64;
;     E(acc, cur, wr, wc, fr, fq, sR);
;     if (!has_next) break;
	s_waitcnt lgkmcnt(0)
	s_setprio 1
	s_waitcnt lgkmcnt(0)
	v_mfma_f32_16x16x32_bf16 v[62:65], v[130:133], v[164:167], v[62:65]
	v_mfma_f32_16x16x32_bf16 v[58:61], v[156:159], v[164:167], v[58:61]
	v_mfma_f32_16x16x32_bf16 v[46:49], v[130:133], v[172:175], v[46:49]
	v_mfma_f32_16x16x32_bf16 v[42:45], v[156:159], v[172:175], v[42:45]
	v_mfma_f32_16x16x32_bf16 v[30:33], v[130:133], v[180:183], v[30:33]
	v_mfma_f32_16x16x32_bf16 v[26:29], v[156:159], v[180:183], v[26:29]
	v_mfma_f32_16x16x32_bf16 v[14:17], v[130:133], v[188:191], v[14:17]
	v_mfma_f32_16x16x32_bf16 v[10:13], v[156:159], v[188:191], v[10:13]
	v_mfma_f32_16x16x32_bf16 v[62:65], v[152:155], v[168:171], v[62:65]
	v_mfma_f32_16x16x32_bf16 v[58:61], v[160:163], v[168:171], v[58:61]
	v_mfma_f32_16x16x32_bf16 v[46:49], v[152:155], v[176:179], v[46:49]
	v_mfma_f32_16x16x32_bf16 v[42:45], v[160:163], v[176:179], v[42:45]
	v_mfma_f32_16x16x32_bf16 v[30:33], v[152:155], v[184:187], v[30:33]
	v_mfma_f32_16x16x32_bf16 v[26:29], v[160:163], v[184:187], v[26:29]
	v_mfma_f32_16x16x32_bf16 v[14:17], v[152:155], v[192:195], v[14:17]
	v_mfma_f32_16x16x32_bf16 v[10:13], v[160:163], v[192:195], v[10:13]
	s_setprio 0
	s_barrier
	s_add_i32 s56, s56, s65
	v_lshl_add_u64 v[130:131], v[246:247], 0, s[86:87]
	s_mov_b32 m0, s56
	s_nop 0
	global_load_lds_dwordx4 v[130:131], off
	v_lshl_add_u64 v[130:131], v[248:249], 0, s[86:87]
	s_add_i32 m0, s56, 0x2000
	s_nop 0
	global_load_lds_dwordx4 v[130:131], off
	s_waitcnt vmcnt(6)
	s_barrier
	s_setprio 1
	v_mfma_f32_16x16x32_bf16 v[54:57], v[196:199], v[164:167], v[54:57]
	v_mfma_f32_16x16x32_bf16 v[50:53], v[230:233], v[164:167], v[50:53]
	v_mfma_f32_16x16x32_bf16 v[38:41], v[196:199], v[172:175], v[38:41]
	v_mfma_f32_16x16x32_bf16 v[34:37], v[230:233], v[172:175], v[34:37]
	v_mfma_f32_16x16x32_bf16 v[22:25], v[196:199], v[180:183], v[22:25]
	v_mfma_f32_16x16x32_bf16 v[18:21], v[230:233], v[180:183], v[18:21]
	v_mfma_f32_16x16x32_bf16 v[6:9], v[196:199], v[188:191], v[6:9]
	v_mfma_f32_16x16x32_bf16 v[2:5], v[230:233], v[188:191], v[2:5]
	v_mfma_f32_16x16x32_bf16 v[54:57], v[226:229], v[168:171], v[54:57]
	v_mfma_f32_16x16x32_bf16 v[50:53], v[234:237], v[168:171], v[50:53]
	v_mfma_f32_16x16x32_bf16 v[38:41], v[226:229], v[176:179], v[38:41]
	v_mfma_f32_16x16x32_bf16 v[34:37], v[234:237], v[176:179], v[34:37]
	v_mfma_f32_16x16x32_bf16 v[22:25], v[226:229], v[184:187], v[22:25]
	v_mfma_f32_16x16x32_bf16 v[18:21], v[234:237], v[184:187], v[18:21]
	v_mfma_f32_16x16x32_bf16 v[6:9], v[226:229], v[192:195], v[6:9]
	v_mfma_f32_16x16x32_bf16 v[2:5], v[234:237], v[192:195], v[2:5]
	s_setprio 0
	s_add_u32 s44, s44, 0x100
	s_addc_u32 s45, s45, 0
	s_add_u32 s79, s79, 0x100
	s_addc_u32 s80, s80, 0
	s_cmp_ge_u32 s81, s71
	s_mov_b32 s56, s81
	s_barrier
	s_cbranch_scc0 .LBB0_835
	s_and_b64 vcc, exec, s[52:53]
	s_cbranch_vccnz .Lres_x0_path
	v_and_b32_e32 v248, 15, v204
	v_lshrrev_b32_e32 v249, 4, v204
	v_and_b32_e32 v246, 1, v249
	v_lshrrev_b32_e32 v247, 1, v249
	v_lshl_or_b32 v246, v246, 1, v247
	v_lshl_add_u32 v246, v248, 2, v246
	v_lshlrev_b32_e32 v246, 2, v246
	v_and_b32_e32 v248, 3, v204
	v_lshrrev_b32_e32 v249, 2, v204
	v_and_b32_e32 v247, 1, v248
	v_lshrrev_b32_e32 v152, 1, v248
	v_lshl_or_b32 v247, v247, 1, v152
	v_lshl_add_u32 v247, v247, 4, v249
	v_lshlrev_b32_e32 v247, 2, v247
	v_and_b32_e32 v152, 64, v222
	v_add_u32_e32 v152, v152, v249
	v_lshl_add_u32 v152, s78, 8, v152
	v_and_b32_e32 v153, 0x60, v224
	v_lshl_or_b32 v153, v248, 3, v153
	v_lshl_or_b32 v154, s34, 8, v153
	v_lshlrev_b32_e32 v153, 10, v152
	v_add_u32_e32 v154, v154, v153
	v_mov_b32_e32 v155, 0
	v_lshl_add_u64 v[132:133], v[154:155], 1, s[22:23]
	v_mov_b64_e32 v[130:131], v[132:133]
	v_lshl_add_u32 v152, s78, 8, v222
	v_lshlrev_b32_e32 v154, 6, v152
	s_lshl_b32 s56, s34, 4
	s_lshl_b32 s57, s70, 2
	s_add_i32 s56, s56, s57
	v_add_u32_e32 v154, s56, v154
	v_lshl_add_u64 v[250:251], v[154:155], 0, s[92:93]
	s_mov_b32 s57, 0
	global_load_dwordx4 v[152:155], v[130:131], off
	global_load_dwordx4 v[156:159], v[130:131], off offset:256
	s_mov_b32 s56, 0x8000
	v_lshl_add_u64 v[130:131], v[130:131], 0, s[56:57]
	global_load_dwordx4 v[160:163], v[130:131], off
	global_load_dwordx4 v[164:167], v[130:131], off offset:256
	s_mov_b32 s56, 0x8000
	v_lshl_add_u64 v[130:131], v[130:131], 0, s[56:57]
	global_load_dwordx4 v[168:171], v[130:131], off
	global_load_dwordx4 v[172:175], v[130:131], off offset:256
	s_mov_b32 s56, 0x8000
	v_lshl_add_u64 v[130:131], v[130:131], 0, s[56:57]
	global_load_dwordx4 v[176:179], v[130:131], off
	global_load_dwordx4 v[180:183], v[130:131], off offset:256
	s_mov_b32 s56, 0x28000
	v_lshl_add_u64 v[130:131], v[130:131], 0, s[56:57]
	global_load_dwordx4 v[184:187], v[130:131], off
	global_load_dwordx4 v[188:191], v[130:131], off offset:256
	s_mov_b32 s56, 0x8000
	v_lshl_add_u64 v[130:131], v[130:131], 0, s[56:57]
	global_load_dwordx4 v[192:195], v[130:131], off
	global_load_dwordx4 v[196:199], v[130:131], off offset:256
	s_mov_b32 s56, 0x8000
	v_lshl_add_u64 v[130:131], v[130:131], 0, s[56:57]
	global_load_dwordx4 v[226:229], v[130:131], off
	global_load_dwordx4 v[230:233], v[130:131], off offset:256
	s_mov_b32 s56, 0x8000
	v_lshl_add_u64 v[130:131], v[130:131], 0, s[56:57]
	global_load_dwordx4 v[234:237], v[130:131], off
	global_load_dwordx4 v[238:241], v[130:131], off offset:256
	v_permlane16_swap_b32_e32 v126, v122
	v_permlane16_swap_b32_e32 v127, v123
	v_permlane16_swap_b32_e32 v128, v124
	v_permlane16_swap_b32_e32 v129, v125
	v_permlane16_swap_b32_e32 v118, v114
	v_permlane16_swap_b32_e32 v119, v115
	v_permlane16_swap_b32_e32 v120, v116
	v_permlane16_swap_b32_e32 v121, v117
; DI unsigned pk2(float lo, float hi) { f32x2 v = {lo, hi}; bf2_t r = __builtin_convertvector(v, bf2_t); return __builtin_bit_cast(unsigned, r); }
; DI float bflo(unsigned u) { return __uint_as_float(u << 16); }
; DI float bfhi(unsigned u) { return __uint_as_float(u & 0xffff0000u); }
;   DI void operator()(const f32x4 (&acc)[2][2][4][2], const Unit& u, int wr, int wc, int fr, int fq, const PG8_LAS float* sR) const {
;     ...
; #pragma unroll
;       for (int m = 0; m < 4; ++m) {
;         const int row = row0 + ai * HALF + m * 16;
;         const size_t ro = (size_t)row * 1024 + col0;
;         float ss = 0.f;
; #pragma unroll
;         for (int bj = 0; bj < 2; ++bj)
; #pragma unroll
;           for (int n = 0; n < 2; ++n) {
;             f32x4 v;
;             if (X0 != nullptr) v = *(const f32x4*)(X0 + ro + bj * HALF + n * 16);
;             else { const u32x2 q = sv[m][bj][n]; v[0] = bflo(q[0]); v[1] = bfhi(q[0]); v[2] = bflo(q[1]); v[3] = bfhi(q[1]); }
;             v += acc[ai][bj][m][n];
;             ss += v[0] * v[0] + v[1] * v[1] + v[2] * v[2] + v[3] * v[3];
;             if (!dry) { u32x2 q; q[0] = pk2(v[0], v[1]); q[1] = pk2(v[2], v[3]); *(u32x2*)(S + ro + bj * HALF + n * 16) = q; }
;           }
;         ss += __shfl_xor(ss, 16); ss += __shfl_xor(ss, 32);
;         if (!dry && fq == 0) ssq[(size_t)row * 16 + u.pn * 4 + wc] = ss;
	v_permlane16_swap_b32_e32 v110, v106
	v_permlane16_swap_b32_e32 v111, v107
	v_permlane16_swap_b32_e32 v112, v108
	v_permlane16_swap_b32_e32 v113, v109
	v_permlane16_swap_b32_e32 v102, v98
	v_permlane16_swap_b32_e32 v103, v99
	v_permlane16_swap_b32_e32 v104, v100
	v_permlane16_swap_b32_e32 v105, v101
	v_permlane16_swap_b32_e32 v94, v90
	v_permlane16_swap_b32_e32 v95, v91
	v_permlane16_swap_b32_e32 v96, v92
	v_permlane16_swap_b32_e32 v97, v93
	v_permlane16_swap_b32_e32 v86, v82
	v_permlane16_swap_b32_e32 v87, v83
	v_permlane16_swap_b32_e32 v88, v84
	v_permlane16_swap_b32_e32 v89, v85
	v_permlane16_swap_b32_e32 v78, v74
	v_permlane16_swap_b32_e32 v79, v75
	v_permlane16_swap_b32_e32 v80, v76
	v_permlane16_swap_b32_e32 v81, v77
	v_permlane16_swap_b32_e32 v70, v66
	v_permlane16_swap_b32_e32 v71, v67
	v_permlane16_swap_b32_e32 v72, v68
	v_permlane16_swap_b32_e32 v73, v69
	v_permlane16_swap_b32_e32 v62, v58
	v_permlane16_swap_b32_e32 v63, v59
	v_permlane16_swap_b32_e32 v64, v60
	v_permlane16_swap_b32_e32 v65, v61
	v_permlane16_swap_b32_e32 v54, v50
	v_permlane16_swap_b32_e32 v55, v51
	v_permlane16_swap_b32_e32 v56, v52
	v_permlane16_swap_b32_e32 v57, v53
	v_permlane16_swap_b32_e32 v46, v42
	v_permlane16_swap_b32_e32 v47, v43
	v_permlane16_swap_b32_e32 v48, v44
	v_permlane16_swap_b32_e32 v49, v45
	v_permlane16_swap_b32_e32 v38, v34
	v_permlane16_swap_b32_e32 v39, v35
	v_permlane16_swap_b32_e32 v40, v36
	v_permlane16_swap_b32_e32 v41, v37
	v_permlane16_swap_b32_e32 v30, v26
	v_permlane16_swap_b32_e32 v31, v27
	v_permlane16_swap_b32_e32 v32, v28
	v_permlane16_swap_b32_e32 v33, v29
	v_permlane16_swap_b32_e32 v22, v18
	v_permlane16_swap_b32_e32 v23, v19
	v_permlane16_swap_b32_e32 v24, v20
	v_permlane16_swap_b32_e32 v25, v21
	v_permlane16_swap_b32_e32 v14, v10
	v_permlane16_swap_b32_e32 v15, v11
	v_permlane16_swap_b32_e32 v16, v12
	v_permlane16_swap_b32_e32 v17, v13
	v_permlane16_swap_b32_e32 v6, v2
	v_permlane16_swap_b32_e32 v7, v3
	v_permlane16_swap_b32_e32 v8, v4
	v_permlane16_swap_b32_e32 v9, v5
	s_waitcnt vmcnt(15)
	ds_bpermute_b32 v152, v246, v152
	ds_bpermute_b32 v153, v246, v153
	ds_bpermute_b32 v154, v246, v154
	ds_bpermute_b32 v155, v246, v155
	s_waitcnt vmcnt(14)
	ds_bpermute_b32 v156, v246, v156
	ds_bpermute_b32 v157, v246, v157
	ds_bpermute_b32 v158, v246, v158
	ds_bpermute_b32 v159, v246, v159
	s_waitcnt lgkmcnt(4)
	v_lshlrev_b32_e32 v242, 16, v152
	v_and_b32_e32 v243, 0xffff0000, v152
	v_lshlrev_b32_e32 v244, 16, v153
	v_and_b32_e32 v245, 0xffff0000, v153
	v_pk_add_f32 v[126:127], v[126:127], v[242:243]
	v_pk_add_f32 v[128:129], v[128:129], v[244:245]
	v_lshlrev_b32_e32 v242, 16, v154
	v_and_b32_e32 v243, 0xffff0000, v154
	v_lshlrev_b32_e32 v244, 16, v155
	v_and_b32_e32 v245, 0xffff0000, v155
	v_pk_add_f32 v[122:123], v[122:123], v[242:243]
	v_pk_add_f32 v[124:125], v[124:125], v[244:245]
	v_mul_f32_e32 v130, v126, v126
	v_mul_f32_e32 v131, v127, v127
	v_fmac_f32_e32 v130, v128, v128
	v_fmac_f32_e32 v131, v129, v129
	v_fmac_f32_e32 v130, v122, v122
	v_fmac_f32_e32 v131, v123, v123
	v_fmac_f32_e32 v130, v124, v124
	v_fmac_f32_e32 v131, v125, v125
	v_cvt_pk_bf16_f32 v126, v126, v127
	v_cvt_pk_bf16_f32 v127, v128, v129
	v_cvt_pk_bf16_f32 v128, v122, v123
	v_cvt_pk_bf16_f32 v129, v124, v125
	ds_bpermute_b32 v126, v247, v126
	ds_bpermute_b32 v127, v247, v127
	ds_bpermute_b32 v128, v247, v128
	ds_bpermute_b32 v129, v247, v129
	s_waitcnt vmcnt(13)
	ds_bpermute_b32 v160, v246, v160
	ds_bpermute_b32 v161, v246, v161
	ds_bpermute_b32 v162, v246, v162
	ds_bpermute_b32 v163, v246, v163
	s_waitcnt lgkmcnt(8)
	v_lshlrev_b32_e32 v242, 16, v156
	v_and_b32_e32 v243, 0xffff0000, v156
	v_lshlrev_b32_e32 v244, 16, v157
	v_and_b32_e32 v245, 0xffff0000, v157
	v_pk_add_f32 v[118:119], v[118:119], v[242:243]
	v_pk_add_f32 v[120:121], v[120:121], v[244:245]
	v_lshlrev_b32_e32 v242, 16, v158
	v_and_b32_e32 v243, 0xffff0000, v158
	v_lshlrev_b32_e32 v244, 16, v159
	v_and_b32_e32 v245, 0xffff0000, v159
	v_pk_add_f32 v[114:115], v[114:115], v[242:243]
	v_pk_add_f32 v[116:117], v[116:117], v[244:245]
	v_fmac_f32_e32 v130, v118, v118
	v_fmac_f32_e32 v131, v119, v119
	v_fmac_f32_e32 v130, v120, v120
	v_fmac_f32_e32 v131, v121, v121
	v_fmac_f32_e32 v130, v114, v114
	v_fmac_f32_e32 v131, v115, v115
	v_fmac_f32_e32 v130, v116, v116
	v_fmac_f32_e32 v131, v117, v117
	v_cvt_pk_bf16_f32 v118, v118, v119
	v_cvt_pk_bf16_f32 v119, v120, v121
	v_cvt_pk_bf16_f32 v120, v114, v115
	v_cvt_pk_bf16_f32 v121, v116, v117
	ds_bpermute_b32 v118, v247, v118
	ds_bpermute_b32 v119, v247, v119
	ds_bpermute_b32 v120, v247, v120
	ds_bpermute_b32 v121, v247, v121
	v_add_f32_e32 v130, v130, v131
	v_mov_b32_e32 v131, v130
	s_nop 1
	v_permlane16_swap_b32_e32 v130, v131
	s_nop 1
	v_add_f32_e32 v130, v130, v131
	v_mov_b32_e32 v131, v130
	s_nop 1
	v_permlane32_swap_b32_e32 v130, v131
	s_nop 1
	v_add_f32_e32 v130, v130, v131
	s_and_saveexec_b64 s[58:59], s[40:41]
	global_store_dword v[250:251], v130, off
	s_or_b64 exec, exec, s[58:59]
	s_mov_b32 s56, 0x400
	v_lshl_add_u64 v[250:251], v[250:251], 0, s[56:57]
	s_waitcnt vmcnt(13)
	ds_bpermute_b32 v164, v246, v164
	ds_bpermute_b32 v165, v246, v165
	ds_bpermute_b32 v166, v246, v166
	ds_bpermute_b32 v167, v246, v167
	s_waitcnt lgkmcnt(12)
	global_store_dwordx4 v[132:133], v[126:129], off
	s_waitcnt lgkmcnt(8)
; DI unsigned pk2(float lo, float hi) { f32x2 v = {lo, hi}; bf2_t r = __builtin_convertvector(v, bf2_t); return __builtin_bit_cast(unsigned, r); }
; DI float bflo(unsigned u) { return __uint_as_float(u << 16); }
; DI float bfhi(unsigned u) { return __uint_as_float(u & 0xffff0000u); }
;   DI void operator()(const f32x4 (&acc)[2][2][4][2], const Unit& u, int wr, int wc, int fr, int fq, const PG8_LAS float* sR) const {
;     ...
; #pragma unroll
;       for (int m = 0; m < 4; ++m) {
;         const int row = row0 + ai * HALF + m * 16;
;         const size_t ro = (size_t)row * 1024 + col0;
;         float ss = 0.f;
; #pragma unroll
;         for (int bj = 0; bj < 2; ++bj)
; #pragma unroll
;           for (int n = 0; n < 2; ++n) {
;             f32x4 v;
;             if (X0 != nullptr) v = *(const f32x4*)(X0 + ro + bj * HALF + n * 16);
;             else { const u32x2 q = sv[m][bj][n]; v[0] = bflo(q[0]); v[1] = bfhi(q[0]); v[2] = bflo(q[1]); v[3] = bfhi(q[1]); }
;             v += acc[ai][bj][m][n];
;             ss += v[0] * v[0] + v[1] * v[1] + v[2] * v[2] + v[3] * v[3];
;             if (!dry) { u32x2 q; q[0] = pk2(v[0], v[1]); q[1] = pk2(v[2], v[3]); *(u32x2*)(S + ro + bj * HALF + n * 16) = q; }
;           }
;         ss += __shfl_xor(ss, 16); ss += __shfl_xor(ss, 32);
;         if (!dry && fq == 0) ssq[(size_t)row * 16 + u.pn * 4 + wc] = ss;
	v_lshlrev_b32_e32 v242, 16, v160
	v_and_b32_e32 v243, 0xffff0000, v160
	v_lshlrev_b32_e32 v244, 16, v161
	v_and_b32_e32 v245, 0xffff0000, v161
	v_pk_add_f32 v[110:111], v[110:111], v[242:243]
	v_pk_add_f32 v[112:113], v[112:113], v[244:245]
	v_lshlrev_b32_e32 v242, 16, v162
	v_and_b32_e32 v243, 0xffff0000, v162
	v_lshlrev_b32_e32 v244, 16, v163
	v_and_b32_e32 v245, 0xffff0000, v163
	v_pk_add_f32 v[106:107], v[106:107], v[242:243]
	v_pk_add_f32 v[108:109], v[108:109], v[244:245]
	v_mul_f32_e32 v130, v110, v110
	v_mul_f32_e32 v131, v111, v111
	v_fmac_f32_e32 v130, v112, v112
	v_fmac_f32_e32 v131, v113, v113
	v_fmac_f32_e32 v130, v106, v106
	v_fmac_f32_e32 v131, v107, v107
	v_fmac_f32_e32 v130, v108, v108
	v_fmac_f32_e32 v131, v109, v109
	v_cvt_pk_bf16_f32 v110, v110, v111
	v_cvt_pk_bf16_f32 v111, v112, v113
	v_cvt_pk_bf16_f32 v112, v106, v107
	v_cvt_pk_bf16_f32 v113, v108, v109
	ds_bpermute_b32 v110, v247, v110
	ds_bpermute_b32 v111, v247, v111
	ds_bpermute_b32 v112, v247, v112
	ds_bpermute_b32 v113, v247, v113
	s_waitcnt vmcnt(13)
	ds_bpermute_b32 v168, v246, v168
	ds_bpermute_b32 v169, v246, v169
	ds_bpermute_b32 v170, v246, v170
	ds_bpermute_b32 v171, v246, v171
	s_waitcnt lgkmcnt(12)
	global_store_dwordx4 v[132:133], v[118:121], off offset:256
	s_mov_b32 s56, 0x8000
	v_lshl_add_u64 v[132:133], v[132:133], 0, s[56:57]
	s_waitcnt lgkmcnt(8)
	v_lshlrev_b32_e32 v242, 16, v164
	v_and_b32_e32 v243, 0xffff0000, v164
	v_lshlrev_b32_e32 v244, 16, v165
	v_and_b32_e32 v245, 0xffff0000, v165
	v_pk_add_f32 v[102:103], v[102:103], v[242:243]
	v_pk_add_f32 v[104:105], v[104:105], v[244:245]
	v_lshlrev_b32_e32 v242, 16, v166
	v_and_b32_e32 v243, 0xffff0000, v166
	v_lshlrev_b32_e32 v244, 16, v167
	v_and_b32_e32 v245, 0xffff0000, v167
	v_pk_add_f32 v[98:99], v[98:99], v[242:243]
	v_pk_add_f32 v[100:101], v[100:101], v[244:245]
	v_fmac_f32_e32 v130, v102, v102
	v_fmac_f32_e32 v131, v103, v103
	v_fmac_f32_e32 v130, v104, v104
	v_fmac_f32_e32 v131, v105, v105
	v_fmac_f32_e32 v130, v98, v98
	v_fmac_f32_e32 v131, v99, v99
	v_fmac_f32_e32 v130, v100, v100
	v_fmac_f32_e32 v131, v101, v101
	v_cvt_pk_bf16_f32 v102, v102, v103
	v_cvt_pk_bf16_f32 v103, v104, v105
	v_cvt_pk_bf16_f32 v104, v98, v99
	v_cvt_pk_bf16_f32 v105, v100, v101
	ds_bpermute_b32 v102, v247, v102
	ds_bpermute_b32 v103, v247, v103
	ds_bpermute_b32 v104, v247, v104
	ds_bpermute_b32 v105, v247, v105
	v_add_f32_e32 v130, v130, v131
	v_mov_b32_e32 v131, v130
	s_nop 1
	v_permlane16_swap_b32_e32 v130, v131
	s_nop 1
	v_add_f32_e32 v130, v130, v131
	v_mov_b32_e32 v131, v130
	s_nop 1
	v_permlane32_swap_b32_e32 v130, v131
	s_nop 1
	v_add_f32_e32 v130, v130, v131
	s_and_saveexec_b64 s[58:59], s[40:41]
	global_store_dword v[250:251], v130, off
	s_or_b64 exec, exec, s[58:59]
	s_mov_b32 s56, 0x400
	v_lshl_add_u64 v[250:251], v[250:251], 0, s[56:57]
	s_waitcnt vmcnt(14)
	ds_bpermute_b32 v172, v246, v172
	ds_bpermute_b32 v173, v246, v173
	ds_bpermute_b32 v174, v246, v174
	ds_bpermute_b32 v175, v246, v175
	s_waitcnt lgkmcnt(12)
	global_store_dwordx4 v[132:133], v[110:113], off
	s_waitcnt lgkmcnt(8)
	v_lshlrev_b32_e32 v242, 16, v168
	v_and_b32_e32 v243, 0xffff0000, v168
	v_lshlrev_b32_e32 v244, 16, v169
	v_and_b32_e32 v245, 0xffff0000, v169
	v_pk_add_f32 v[94:95], v[94:95], v[242:243]
	v_pk_add_f32 v[96:97], v[96:97], v[244:245]
	v_lshlrev_b32_e32 v242, 16, v170
	v_and_b32_e32 v243, 0xffff0000, v170
	v_lshlrev_b32_e32 v244, 16, v171
	v_and_b32_e32 v245, 0xffff0000, v171
	v_pk_add_f32 v[90:91], v[90:91], v[242:243]
	v_pk_add_f32 v[92:93], v[92:93], v[244:245]
	v_mul_f32_e32 v130, v94, v94
	v_mul_f32_e32 v131, v95, v95
	v_fmac_f32_e32 v130, v96, v96
	v_fmac_f32_e32 v131, v97, v97
	v_fmac_f32_e32 v130, v90, v90
	v_fmac_f32_e32 v131, v91, v91
	v_fmac_f32_e32 v130, v92, v92
	v_fmac_f32_e32 v131, v93, v93
	v_cvt_pk_bf16_f32 v94, v94, v95
	v_cvt_pk_bf16_f32 v95, v96, v97
	v_cvt_pk_bf16_f32 v96, v90, v91
	v_cvt_pk_bf16_f32 v97, v92, v93
	ds_bpermute_b32 v94, v247, v94
	ds_bpermute_b32 v95, v247, v95
	ds_bpermute_b32 v96, v247, v96
	ds_bpermute_b32 v97, v247, v97
	s_waitcnt vmcnt(14)
	ds_bpermute_b32 v176, v246, v176
	ds_bpermute_b32 v177, v246, v177
	ds_bpermute_b32 v178, v246, v178
	ds_bpermute_b32 v179, v246, v179
	s_waitcnt lgkmcnt(12)
	global_store_dwordx4 v[132:133], v[102:105], off offset:256
	s_mov_b32 s56, 0x8000
	v_lshl_add_u64 v[132:133], v[132:133], 0, s[56:57]
	s_waitcnt lgkmcnt(8)
	v_lshlrev_b32_e32 v242, 16, v172
	v_and_b32_e32 v243, 0xffff0000, v172
	v_lshlrev_b32_e32 v244, 16, v173
	v_and_b32_e32 v245, 0xffff0000, v173
	v_pk_add_f32 v[86:87], v[86:87], v[242:243]
	v_pk_add_f32 v[88:89], v[88:89], v[244:245]
	v_lshlrev_b32_e32 v242, 16, v174
	v_and_b32_e32 v243, 0xffff0000, v174
	v_lshlrev_b32_e32 v244, 16, v175
	v_and_b32_e32 v245, 0xffff0000, v175
	v_pk_add_f32 v[82:83], v[82:83], v[242:243]
	v_pk_add_f32 v[84:85], v[84:85], v[244:245]
	v_fmac_f32_e32 v130, v86, v86
	v_fmac_f32_e32 v131, v87, v87
	v_fmac_f32_e32 v130, v88, v88
	v_fmac_f32_e32 v131, v89, v89
	v_fmac_f32_e32 v130, v82, v82
	v_fmac_f32_e32 v131, v83, v83
	v_fmac_f32_e32 v130, v84, v84
	v_fmac_f32_e32 v131, v85, v85
	v_cvt_pk_bf16_f32 v86, v86, v87
	v_cvt_pk_bf16_f32 v87, v88, v89
	v_cvt_pk_bf16_f32 v88, v82, v83
	v_cvt_pk_bf16_f32 v89, v84, v85
	ds_bpermute_b32 v86, v247, v86
	ds_bpermute_b32 v87, v247, v87
	ds_bpermute_b32 v88, v247, v88
	ds_bpermute_b32 v89, v247, v89
	v_add_f32_e32 v130, v130, v131
	v_mov_b32_e32 v131, v130
	s_nop 1
	v_permlane16_swap_b32_e32 v130, v131
	s_nop 1
	v_add_f32_e32 v130, v130, v131
	v_mov_b32_e32 v131, v130
	s_nop 1
	v_permlane32_swap_b32_e32 v130, v131
	s_nop 1
	v_add_f32_e32 v130, v130, v131
	s_and_saveexec_b64 s[58:59], s[40:41]
	global_store_dword v[250:251], v130, off
	s_or_b64 exec, exec, s[58:59]
	s_mov_b32 s56, 0x400
	v_lshl_add_u64 v[250:251], v[250:251], 0, s[56:57]
	s_waitcnt vmcnt(15)
; DI unsigned pk2(float lo, float hi) { f32x2 v = {lo, hi}; bf2_t r = __builtin_convertvector(v, bf2_t); return __builtin_bit_cast(unsigned, r); }
; DI float bflo(unsigned u) { return __uint_as_float(u << 16); }
; DI float bfhi(unsigned u) { return __uint_as_float(u & 0xffff0000u); }
;   DI void operator()(const f32x4 (&acc)[2][2][4][2], const Unit& u, int wr, int wc, int fr, int fq, const PG8_LAS float* sR) const {
;     ...
; #pragma unroll
;       for (int m = 0; m < 4; ++m) {
;         const int row = row0 + ai * HALF + m * 16;
;         const size_t ro = (size_t)row * 1024 + col0;
;         float ss = 0.f;
; #pragma unroll
;         for (int bj = 0; bj < 2; ++bj)
; #pragma unroll
;           for (int n = 0; n < 2; ++n) {
;             f32x4 v;
;             if (X0 != nullptr) v = *(const f32x4*)(X0 + ro + bj * HALF + n * 16);
;             else { const u32x2 q = sv[m][bj][n]; v[0] = bflo(q[0]); v[1] = bfhi(q[0]); v[2] = bflo(q[1]); v[3] = bfhi(q[1]); }
;             v += acc[ai][bj][m][n];
;             ss += v[0] * v[0] + v[1] * v[1] + v[2] * v[2] + v[3] * v[3];
;             if (!dry) { u32x2 q; q[0] = pk2(v[0], v[1]); q[1] = pk2(v[2], v[3]); *(u32x2*)(S + ro + bj * HALF + n * 16) = q; }
;           }
;         ss += __shfl_xor(ss, 16); ss += __shfl_xor(ss, 32);
;         if (!dry && fq == 0) ssq[(size_t)row * 16 + u.pn * 4 + wc] = ss;
	ds_bpermute_b32 v180, v246, v180
	ds_bpermute_b32 v181, v246, v181
	ds_bpermute_b32 v182, v246, v182
	ds_bpermute_b32 v183, v246, v183
	s_waitcnt lgkmcnt(12)
	global_store_dwordx4 v[132:133], v[94:97], off
	s_waitcnt lgkmcnt(8)
	v_lshlrev_b32_e32 v242, 16, v176
	v_and_b32_e32 v243, 0xffff0000, v176
	v_lshlrev_b32_e32 v244, 16, v177
	v_and_b32_e32 v245, 0xffff0000, v177
	v_pk_add_f32 v[78:79], v[78:79], v[242:243]
	v_pk_add_f32 v[80:81], v[80:81], v[244:245]
	v_lshlrev_b32_e32 v242, 16, v178
	v_and_b32_e32 v243, 0xffff0000, v178
	v_lshlrev_b32_e32 v244, 16, v179
	v_and_b32_e32 v245, 0xffff0000, v179
	v_pk_add_f32 v[74:75], v[74:75], v[242:243]
	v_pk_add_f32 v[76:77], v[76:77], v[244:245]
	v_mul_f32_e32 v130, v78, v78
	v_mul_f32_e32 v131, v79, v79
	v_fmac_f32_e32 v130, v80, v80
	v_fmac_f32_e32 v131, v81, v81
	v_fmac_f32_e32 v130, v74, v74
	v_fmac_f32_e32 v131, v75, v75
	v_fmac_f32_e32 v130, v76, v76
	v_fmac_f32_e32 v131, v77, v77
	v_cvt_pk_bf16_f32 v78, v78, v79
	v_cvt_pk_bf16_f32 v79, v80, v81
	v_cvt_pk_bf16_f32 v80, v74, v75
	v_cvt_pk_bf16_f32 v81, v76, v77
	ds_bpermute_b32 v78, v247, v78
	ds_bpermute_b32 v79, v247, v79
	ds_bpermute_b32 v80, v247, v80
	ds_bpermute_b32 v81, v247, v81
	s_waitcnt vmcnt(15)
	ds_bpermute_b32 v184, v246, v184
	ds_bpermute_b32 v185, v246, v185
	ds_bpermute_b32 v186, v246, v186
	ds_bpermute_b32 v187, v246, v187
	s_waitcnt lgkmcnt(12)
	global_store_dwordx4 v[132:133], v[86:89], off offset:256
	s_mov_b32 s56, 0x8000
	v_lshl_add_u64 v[132:133], v[132:133], 0, s[56:57]
	s_waitcnt lgkmcnt(8)
	v_lshlrev_b32_e32 v242, 16, v180
	v_and_b32_e32 v243, 0xffff0000, v180
	v_lshlrev_b32_e32 v244, 16, v181
	v_and_b32_e32 v245, 0xffff0000, v181
	v_pk_add_f32 v[70:71], v[70:71], v[242:243]
	v_pk_add_f32 v[72:73], v[72:73], v[244:245]
	v_lshlrev_b32_e32 v242, 16, v182
	v_and_b32_e32 v243, 0xffff0000, v182
	v_lshlrev_b32_e32 v244, 16, v183
	v_and_b32_e32 v245, 0xffff0000, v183
	v_pk_add_f32 v[66:67], v[66:67], v[242:243]
	v_pk_add_f32 v[68:69], v[68:69], v[244:245]
	v_fmac_f32_e32 v130, v70, v70
	v_fmac_f32_e32 v131, v71, v71
	v_fmac_f32_e32 v130, v72, v72
	v_fmac_f32_e32 v131, v73, v73
	v_fmac_f32_e32 v130, v66, v66
	v_fmac_f32_e32 v131, v67, v67
	v_fmac_f32_e32 v130, v68, v68
	v_fmac_f32_e32 v131, v69, v69
	v_cvt_pk_bf16_f32 v70, v70, v71
	v_cvt_pk_bf16_f32 v71, v72, v73
	v_cvt_pk_bf16_f32 v72, v66, v67
	v_cvt_pk_bf16_f32 v73, v68, v69
	ds_bpermute_b32 v70, v247, v70
	ds_bpermute_b32 v71, v247, v71
	ds_bpermute_b32 v72, v247, v72
	ds_bpermute_b32 v73, v247, v73
	v_add_f32_e32 v130, v130, v131
	v_mov_b32_e32 v131, v130
	s_nop 1
	v_permlane16_swap_b32_e32 v130, v131
	s_nop 1
	v_add_f32_e32 v130, v130, v131
	v_mov_b32_e32 v131, v130
	s_nop 1
	v_permlane32_swap_b32_e32 v130, v131
	s_nop 1
	v_add_f32_e32 v130, v130, v131
	s_and_saveexec_b64 s[58:59], s[40:41]
	global_store_dword v[250:251], v130, off
	s_or_b64 exec, exec, s[58:59]
	s_mov_b32 s56, 0x1400
	v_lshl_add_u64 v[250:251], v[250:251], 0, s[56:57]
	s_waitcnt vmcnt(16)
	ds_bpermute_b32 v188, v246, v188
	ds_bpermute_b32 v189, v246, v189
	ds_bpermute_b32 v190, v246, v190
	ds_bpermute_b32 v191, v246, v191
	s_waitcnt lgkmcnt(12)
	global_store_dwordx4 v[132:133], v[78:81], off
	s_waitcnt lgkmcnt(8)
	v_lshlrev_b32_e32 v242, 16, v184
	v_and_b32_e32 v243, 0xffff0000, v184
	v_lshlrev_b32_e32 v244, 16, v185
	v_and_b32_e32 v245, 0xffff0000, v185
	v_pk_add_f32 v[62:63], v[62:63], v[242:243]
	v_pk_add_f32 v[64:65], v[64:65], v[244:245]
	v_lshlrev_b32_e32 v242, 16, v186
	v_and_b32_e32 v243, 0xffff0000, v186
	v_lshlrev_b32_e32 v244, 16, v187
	v_and_b32_e32 v245, 0xffff0000, v187
	v_pk_add_f32 v[58:59], v[58:59], v[242:243]
	v_pk_add_f32 v[60:61], v[60:61], v[244:245]
	v_mul_f32_e32 v130, v62, v62
	v_mul_f32_e32 v131, v63, v63
	v_fmac_f32_e32 v130, v64, v64
	v_fmac_f32_e32 v131, v65, v65
	v_fmac_f32_e32 v130, v58, v58
	v_fmac_f32_e32 v131, v59, v59
	v_fmac_f32_e32 v130, v60, v60
	v_fmac_f32_e32 v131, v61, v61
	v_cvt_pk_bf16_f32 v62, v62, v63
	v_cvt_pk_bf16_f32 v63, v64, v65
	v_cvt_pk_bf16_f32 v64, v58, v59
	v_cvt_pk_bf16_f32 v65, v60, v61
	ds_bpermute_b32 v62, v247, v62
	ds_bpermute_b32 v63, v247, v63
	ds_bpermute_b32 v64, v247, v64
	ds_bpermute_b32 v65, v247, v65
	s_waitcnt vmcnt(16)
	ds_bpermute_b32 v192, v246, v192
	ds_bpermute_b32 v193, v246, v193
	ds_bpermute_b32 v194, v246, v194
	ds_bpermute_b32 v195, v246, v195
	s_waitcnt lgkmcnt(12)
	global_store_dwordx4 v[132:133], v[70:73], off offset:256
	s_mov_b32 s56, 0x28000
	v_lshl_add_u64 v[132:133], v[132:133], 0, s[56:57]
	s_waitcnt lgkmcnt(8)
	v_lshlrev_b32_e32 v242, 16, v188
	v_and_b32_e32 v243, 0xffff0000, v188
	v_lshlrev_b32_e32 v244, 16, v189
	v_and_b32_e32 v245, 0xffff0000, v189
	v_pk_add_f32 v[54:55], v[54:55], v[242:243]
	v_pk_add_f32 v[56:57], v[56:57], v[244:245]
	v_lshlrev_b32_e32 v242, 16, v190
	v_and_b32_e32 v243, 0xffff0000, v190
	v_lshlrev_b32_e32 v244, 16, v191
	v_and_b32_e32 v245, 0xffff0000, v191
	v_pk_add_f32 v[50:51], v[50:51], v[242:243]
	v_pk_add_f32 v[52:53], v[52:53], v[244:245]
	v_fmac_f32_e32 v130, v54, v54
	v_fmac_f32_e32 v131, v55, v55
	v_fmac_f32_e32 v130, v56, v56
	v_fmac_f32_e32 v131, v57, v57
	v_fmac_f32_e32 v130, v50, v50
	v_fmac_f32_e32 v131, v51, v51
	v_fmac_f32_e32 v130, v52, v52
	v_fmac_f32_e32 v131, v53, v53
	v_cvt_pk_bf16_f32 v54, v54, v55
	v_cvt_pk_bf16_f32 v55, v56, v57
	v_cvt_pk_bf16_f32 v56, v50, v51
	v_cvt_pk_bf16_f32 v57, v52, v53
	ds_bpermute_b32 v54, v247, v54
	ds_bpermute_b32 v55, v247, v55
	ds_bpermute_b32 v56, v247, v56
	ds_bpermute_b32 v57, v247, v57
	v_add_f32_e32 v130, v130, v131
	v_mov_b32_e32 v131, v130
	s_nop 1
	v_permlane16_swap_b32_e32 v130, v131
	s_nop 1
	v_add_f32_e32 v130, v130, v131
	v_mov_b32_e32 v131, v130
	s_nop 1
	v_permlane32_swap_b32_e32 v130, v131
	s_nop 1
	v_add_f32_e32 v130, v130, v131
	s_and_saveexec_b64 s[58:59], s[40:41]
	global_store_dword v[250:251], v130, off
	s_or_b64 exec, exec, s[58:59]
	s_mov_b32 s56, 0x400
	v_lshl_add_u64 v[250:251], v[250:251], 0, s[56:57]
	s_waitcnt vmcnt(17)
; DI unsigned pk2(float lo, float hi) { f32x2 v = {lo, hi}; bf2_t r = __builtin_convertvector(v, bf2_t); return __builtin_bit_cast(unsigned, r); }
; DI float bflo(unsigned u) { return __uint_as_float(u << 16); }
; DI float bfhi(unsigned u) { return __uint_as_float(u & 0xffff0000u); }
;   DI void operator()(const f32x4 (&acc)[2][2][4][2], const Unit& u, int wr, int wc, int fr, int fq, const PG8_LAS float* sR) const {
;     ...
; #pragma unroll
;       for (int m = 0; m < 4; ++m) {
;         const int row = row0 + ai * HALF + m * 16;
;         const size_t ro = (size_t)row * 1024 + col0;
;         float ss = 0.f;
; #pragma unroll
;         for (int bj = 0; bj < 2; ++bj)
; #pragma unroll
;           for (int n = 0; n < 2; ++n) {
;             f32x4 v;
;             if (X0 != nullptr) v = *(const f32x4*)(X0 + ro + bj * HALF + n * 16);
;             else { const u32x2 q = sv[m][bj][n]; v[0] = bflo(q[0]); v[1] = bfhi(q[0]); v[2] = bflo(q[1]); v[3] = bfhi(q[1]); }
;             v += acc[ai][bj][m][n];
;             ss += v[0] * v[0] + v[1] * v[1] + v[2] * v[2] + v[3] * v[3];
;             if (!dry) { u32x2 q; q[0] = pk2(v[0], v[1]); q[1] = pk2(v[2], v[3]); *(u32x2*)(S + ro + bj * HALF + n * 16) = q; }
;           }
;         ss += __shfl_xor(ss, 16); ss += __shfl_xor(ss, 32);
;         if (!dry && fq == 0) ssq[(size_t)row * 16 + u.pn * 4 + wc] = ss;
	ds_bpermute_b32 v196, v246, v196
	ds_bpermute_b32 v197, v246, v197
	ds_bpermute_b32 v198, v246, v198
	ds_bpermute_b32 v199, v246, v199
	s_waitcnt lgkmcnt(12)
	global_store_dwordx4 v[132:133], v[62:65], off
	s_waitcnt lgkmcnt(8)
	v_lshlrev_b32_e32 v242, 16, v192
	v_and_b32_e32 v243, 0xffff0000, v192
	v_lshlrev_b32_e32 v244, 16, v193
	v_and_b32_e32 v245, 0xffff0000, v193
	v_pk_add_f32 v[46:47], v[46:47], v[242:243]
	v_pk_add_f32 v[48:49], v[48:49], v[244:245]
	v_lshlrev_b32_e32 v242, 16, v194
	v_and_b32_e32 v243, 0xffff0000, v194
	v_lshlrev_b32_e32 v244, 16, v195
	v_and_b32_e32 v245, 0xffff0000, v195
	v_pk_add_f32 v[42:43], v[42:43], v[242:243]
	v_pk_add_f32 v[44:45], v[44:45], v[244:245]
	v_mul_f32_e32 v130, v46, v46
	v_mul_f32_e32 v131, v47, v47
	v_fmac_f32_e32 v130, v48, v48
	v_fmac_f32_e32 v131, v49, v49
	v_fmac_f32_e32 v130, v42, v42
	v_fmac_f32_e32 v131, v43, v43
	v_fmac_f32_e32 v130, v44, v44
	v_fmac_f32_e32 v131, v45, v45
	v_cvt_pk_bf16_f32 v46, v46, v47
	v_cvt_pk_bf16_f32 v47, v48, v49
	v_cvt_pk_bf16_f32 v48, v42, v43
	v_cvt_pk_bf16_f32 v49, v44, v45
	ds_bpermute_b32 v46, v247, v46
	ds_bpermute_b32 v47, v247, v47
	ds_bpermute_b32 v48, v247, v48
	ds_bpermute_b32 v49, v247, v49
	s_waitcnt vmcnt(17)
	ds_bpermute_b32 v226, v246, v226
	ds_bpermute_b32 v227, v246, v227
	ds_bpermute_b32 v228, v246, v228
	ds_bpermute_b32 v229, v246, v229
	s_waitcnt lgkmcnt(12)
	global_store_dwordx4 v[132:133], v[54:57], off offset:256
	s_mov_b32 s56, 0x8000
	v_lshl_add_u64 v[132:133], v[132:133], 0, s[56:57]
	s_waitcnt lgkmcnt(8)
	v_lshlrev_b32_e32 v242, 16, v196
	v_and_b32_e32 v243, 0xffff0000, v196
	v_lshlrev_b32_e32 v244, 16, v197
	v_and_b32_e32 v245, 0xffff0000, v197
	v_pk_add_f32 v[38:39], v[38:39], v[242:243]
	v_pk_add_f32 v[40:41], v[40:41], v[244:245]
	v_lshlrev_b32_e32 v242, 16, v198
	v_and_b32_e32 v243, 0xffff0000, v198
	v_lshlrev_b32_e32 v244, 16, v199
	v_and_b32_e32 v245, 0xffff0000, v199
	v_pk_add_f32 v[34:35], v[34:35], v[242:243]
	v_pk_add_f32 v[36:37], v[36:37], v[244:245]
	v_fmac_f32_e32 v130, v38, v38
	v_fmac_f32_e32 v131, v39, v39
	v_fmac_f32_e32 v130, v40, v40
	v_fmac_f32_e32 v131, v41, v41
	v_fmac_f32_e32 v130, v34, v34
	v_fmac_f32_e32 v131, v35, v35
	v_fmac_f32_e32 v130, v36, v36
	v_fmac_f32_e32 v131, v37, v37
	v_cvt_pk_bf16_f32 v38, v38, v39
	v_cvt_pk_bf16_f32 v39, v40, v41
	v_cvt_pk_bf16_f32 v40, v34, v35
	v_cvt_pk_bf16_f32 v41, v36, v37
	ds_bpermute_b32 v38, v247, v38
	ds_bpermute_b32 v39, v247, v39
	ds_bpermute_b32 v40, v247, v40
	ds_bpermute_b32 v41, v247, v41
	v_add_f32_e32 v130, v130, v131
	v_mov_b32_e32 v131, v130
	s_nop 1
	v_permlane16_swap_b32_e32 v130, v131
	s_nop 1
	v_add_f32_e32 v130, v130, v131
	v_mov_b32_e32 v131, v130
	s_nop 1
	v_permlane32_swap_b32_e32 v130, v131
	s_nop 1
	v_add_f32_e32 v130, v130, v131
	s_and_saveexec_b64 s[58:59], s[40:41]
	global_store_dword v[250:251], v130, off
	s_or_b64 exec, exec, s[58:59]
	s_mov_b32 s56, 0x400
	v_lshl_add_u64 v[250:251], v[250:251], 0, s[56:57]
	s_waitcnt vmcnt(18)
	ds_bpermute_b32 v230, v246, v230
	ds_bpermute_b32 v231, v246, v231
	ds_bpermute_b32 v232, v246, v232
	ds_bpermute_b32 v233, v246, v233
	s_waitcnt lgkmcnt(12)
	global_store_dwordx4 v[132:133], v[46:49], off
	s_waitcnt lgkmcnt(8)
	v_lshlrev_b32_e32 v242, 16, v226
	v_and_b32_e32 v243, 0xffff0000, v226
	v_lshlrev_b32_e32 v244, 16, v227
	v_and_b32_e32 v245, 0xffff0000, v227
	v_pk_add_f32 v[30:31], v[30:31], v[242:243]
	v_pk_add_f32 v[32:33], v[32:33], v[244:245]
	v_lshlrev_b32_e32 v242, 16, v228
	v_and_b32_e32 v243, 0xffff0000, v228
	v_lshlrev_b32_e32 v244, 16, v229
	v_and_b32_e32 v245, 0xffff0000, v229
	v_pk_add_f32 v[26:27], v[26:27], v[242:243]
	v_pk_add_f32 v[28:29], v[28:29], v[244:245]
	v_mul_f32_e32 v130, v30, v30
	v_mul_f32_e32 v131, v31, v31
	v_fmac_f32_e32 v130, v32, v32
	v_fmac_f32_e32 v131, v33, v33
	v_fmac_f32_e32 v130, v26, v26
	v_fmac_f32_e32 v131, v27, v27
	v_fmac_f32_e32 v130, v28, v28
	v_fmac_f32_e32 v131, v29, v29
	v_cvt_pk_bf16_f32 v30, v30, v31
	v_cvt_pk_bf16_f32 v31, v32, v33
	v_cvt_pk_bf16_f32 v32, v26, v27
	v_cvt_pk_bf16_f32 v33, v28, v29
	ds_bpermute_b32 v30, v247, v30
	ds_bpermute_b32 v31, v247, v31
	ds_bpermute_b32 v32, v247, v32
	ds_bpermute_b32 v33, v247, v33
	s_waitcnt vmcnt(18)
	ds_bpermute_b32 v234, v246, v234
	ds_bpermute_b32 v235, v246, v235
	ds_bpermute_b32 v236, v246, v236
	ds_bpermute_b32 v237, v246, v237
	s_waitcnt lgkmcnt(12)
	global_store_dwordx4 v[132:133], v[38:41], off offset:256
	s_mov_b32 s56, 0x8000
	v_lshl_add_u64 v[132:133], v[132:133], 0, s[56:57]
	s_waitcnt lgkmcnt(8)
; DI unsigned pk2(float lo, float hi) { f32x2 v = {lo, hi}; bf2_t r = __builtin_convertvector(v, bf2_t); return __builtin_bit_cast(unsigned, r); }
; DI float bflo(unsigned u) { return __uint_as_float(u << 16); }
; DI float bfhi(unsigned u) { return __uint_as_float(u & 0xffff0000u); }
;   DI void operator()(const f32x4 (&acc)[2][2][4][2], const Unit& u, int wr, int wc, int fr, int fq, const PG8_LAS float* sR) const {
;     ...
; #pragma unroll
;       for (int m = 0; m < 4; ++m) {
;         const int row = row0 + ai * HALF + m * 16;
;         const size_t ro = (size_t)row * 1024 + col0;
;         float ss = 0.f;
; #pragma unroll
;         for (int bj = 0; bj < 2; ++bj)
; #pragma unroll
;           for (int n = 0; n < 2; ++n) {
;             f32x4 v;
;             if (X0 != nullptr) v = *(const f32x4*)(X0 + ro + bj * HALF + n * 16);
;             else { const u32x2 q = sv[m][bj][n]; v[0] = bflo(q[0]); v[1] = bfhi(q[0]); v[2] = bflo(q[1]); v[3] = bfhi(q[1]); }
;             v += acc[ai][bj][m][n];
;             ss += v[0] * v[0] + v[1] * v[1] + v[2] * v[2] + v[3] * v[3];
;             if (!dry) { u32x2 q; q[0] = pk2(v[0], v[1]); q[1] = pk2(v[2], v[3]); *(u32x2*)(S + ro + bj * HALF + n * 16) = q; }
;           }
;         ss += __shfl_xor(ss, 16); ss += __shfl_xor(ss, 32);
;         if (!dry && fq == 0) ssq[(size_t)row * 16 + u.pn * 4 + wc] = ss;
; template <class Epi>
; DI void gemm_phase(PG8_LAS unsigned char* lds, const Gemm g, const StaticOrder& S, const Epi& E) {
;     ...
;     if (!has_next) break;
; #pragma unroll
;     for (int a = 0; a < 2; ++a)
; #pragma unroll
;       for (int b = 0; b < 2; ++b)
; #pragma unroll
;         for (int m = 0; m < 4; ++m)
; #pragma unroll
;           for (int n = 0; n < 2; ++n) acc[a][b][m][n] = (f32x4){0.f, 0.f, 0.f, 0.f};
;     cur = nxt; cA = nA; cB = nB; ++ui;
	v_lshlrev_b32_e32 v242, 16, v230
	v_and_b32_e32 v243, 0xffff0000, v230
	v_lshlrev_b32_e32 v244, 16, v231
	v_and_b32_e32 v245, 0xffff0000, v231
	v_pk_add_f32 v[22:23], v[22:23], v[242:243]
	v_pk_add_f32 v[24:25], v[24:25], v[244:245]
	v_lshlrev_b32_e32 v242, 16, v232
	v_and_b32_e32 v243, 0xffff0000, v232
	v_lshlrev_b32_e32 v244, 16, v233
	v_and_b32_e32 v245, 0xffff0000, v233
	v_pk_add_f32 v[18:19], v[18:19], v[242:243]
	v_pk_add_f32 v[20:21], v[20:21], v[244:245]
	v_fmac_f32_e32 v130, v22, v22
	v_fmac_f32_e32 v131, v23, v23
	v_fmac_f32_e32 v130, v24, v24
	v_fmac_f32_e32 v131, v25, v25
	v_fmac_f32_e32 v130, v18, v18
	v_fmac_f32_e32 v131, v19, v19
	v_fmac_f32_e32 v130, v20, v20
	v_fmac_f32_e32 v131, v21, v21
	v_cvt_pk_bf16_f32 v22, v22, v23
	v_cvt_pk_bf16_f32 v23, v24, v25
	v_cvt_pk_bf16_f32 v24, v18, v19
	v_cvt_pk_bf16_f32 v25, v20, v21
	ds_bpermute_b32 v22, v247, v22
	ds_bpermute_b32 v23, v247, v23
	ds_bpermute_b32 v24, v247, v24
	ds_bpermute_b32 v25, v247, v25
	v_add_f32_e32 v130, v130, v131
	v_mov_b32_e32 v131, v130
	s_nop 1
	v_permlane16_swap_b32_e32 v130, v131
	s_nop 1
	v_add_f32_e32 v130, v130, v131
	v_mov_b32_e32 v131, v130
	s_nop 1
	v_permlane32_swap_b32_e32 v130, v131
	s_nop 1
	v_add_f32_e32 v130, v130, v131
	s_and_saveexec_b64 s[58:59], s[40:41]
	global_store_dword v[250:251], v130, off
	s_or_b64 exec, exec, s[58:59]
	s_mov_b32 s56, 0x400
	v_lshl_add_u64 v[250:251], v[250:251], 0, s[56:57]
	s_waitcnt vmcnt(19)
	ds_bpermute_b32 v238, v246, v238
	ds_bpermute_b32 v239, v246, v239
	ds_bpermute_b32 v240, v246, v240
	ds_bpermute_b32 v241, v246, v241
	s_waitcnt lgkmcnt(12)
	global_store_dwordx4 v[132:133], v[30:33], off
	s_waitcnt lgkmcnt(8)
	v_lshlrev_b32_e32 v242, 16, v234
	v_and_b32_e32 v243, 0xffff0000, v234
	v_lshlrev_b32_e32 v244, 16, v235
	v_and_b32_e32 v245, 0xffff0000, v235
	v_pk_add_f32 v[14:15], v[14:15], v[242:243]
	v_pk_add_f32 v[16:17], v[16:17], v[244:245]
	v_lshlrev_b32_e32 v242, 16, v236
	v_and_b32_e32 v243, 0xffff0000, v236
	v_lshlrev_b32_e32 v244, 16, v237
	v_and_b32_e32 v245, 0xffff0000, v237
	v_pk_add_f32 v[10:11], v[10:11], v[242:243]
	v_pk_add_f32 v[12:13], v[12:13], v[244:245]
	v_mul_f32_e32 v130, v14, v14
	v_mul_f32_e32 v131, v15, v15
	v_fmac_f32_e32 v130, v16, v16
	v_fmac_f32_e32 v131, v17, v17
	v_fmac_f32_e32 v130, v10, v10
	v_fmac_f32_e32 v131, v11, v11
	v_fmac_f32_e32 v130, v12, v12
	v_fmac_f32_e32 v131, v13, v13
	v_cvt_pk_bf16_f32 v14, v14, v15
	v_cvt_pk_bf16_f32 v15, v16, v17
	v_cvt_pk_bf16_f32 v16, v10, v11
	v_cvt_pk_bf16_f32 v17, v12, v13
	ds_bpermute_b32 v14, v247, v14
	ds_bpermute_b32 v15, v247, v15
	ds_bpermute_b32 v16, v247, v16
	ds_bpermute_b32 v17, v247, v17
	s_waitcnt lgkmcnt(8)
	global_store_dwordx4 v[132:133], v[22:25], off offset:256
	s_mov_b32 s56, 0x8000
	v_lshl_add_u64 v[132:133], v[132:133], 0, s[56:57]
	s_waitcnt lgkmcnt(4)
	v_lshlrev_b32_e32 v242, 16, v238
	v_and_b32_e32 v243, 0xffff0000, v238
	v_lshlrev_b32_e32 v244, 16, v239
	v_and_b32_e32 v245, 0xffff0000, v239
	v_pk_add_f32 v[6:7], v[6:7], v[242:243]
	v_pk_add_f32 v[8:9], v[8:9], v[244:245]
	v_lshlrev_b32_e32 v242, 16, v240
	v_and_b32_e32 v243, 0xffff0000, v240
	v_lshlrev_b32_e32 v244, 16, v241
	v_and_b32_e32 v245, 0xffff0000, v241
	v_pk_add_f32 v[2:3], v[2:3], v[242:243]
	v_pk_add_f32 v[4:5], v[4:5], v[244:245]
	v_fmac_f32_e32 v130, v6, v6
	v_fmac_f32_e32 v131, v7, v7
	v_fmac_f32_e32 v130, v8, v8
	v_fmac_f32_e32 v131, v9, v9
	v_fmac_f32_e32 v130, v2, v2
	v_fmac_f32_e32 v131, v3, v3
	v_fmac_f32_e32 v130, v4, v4
	v_fmac_f32_e32 v131, v5, v5
	v_cvt_pk_bf16_f32 v6, v6, v7
	v_cvt_pk_bf16_f32 v7, v8, v9
	v_cvt_pk_bf16_f32 v8, v2, v3
	v_cvt_pk_bf16_f32 v9, v4, v5
	ds_bpermute_b32 v6, v247, v6
	ds_bpermute_b32 v7, v247, v7
	ds_bpermute_b32 v8, v247, v8
	ds_bpermute_b32 v9, v247, v9
	v_add_f32_e32 v130, v130, v131
	v_mov_b32_e32 v131, v130
	s_nop 1
	v_permlane16_swap_b32_e32 v130, v131
	s_nop 1
	v_add_f32_e32 v130, v130, v131
	v_mov_b32_e32 v131, v130
	s_nop 1
	v_permlane32_swap_b32_e32 v130, v131
	s_nop 1
	v_add_f32_e32 v130, v130, v131
	s_and_saveexec_b64 s[58:59], s[40:41]
	global_store_dword v[250:251], v130, off
	s_or_b64 exec, exec, s[58:59]
	s_waitcnt lgkmcnt(4)
	global_store_dwordx4 v[132:133], v[14:17], off
	s_waitcnt lgkmcnt(0)
	global_store_dwordx4 v[132:133], v[6:9], off offset:256
	v_readlane_b32 s4, v253, 56
	v_readlane_b32 s5, v253, 57
	v_readlane_b32 s6, v253, 58
	v_readlane_b32 s7, v253, 59
	v_readlane_b32 s8, v253, 60
	v_readlane_b32 s9, v253, 61
	v_readlane_b32 s10, v253, 62
	v_readlane_b32 s11, v253, 63
	v_readlane_b32 s12, v254, 0
	v_readlane_b32 s13, v254, 1
	v_readlane_b32 s14, v254, 2
	v_readlane_b32 s15, v254, 3
	v_readlane_b32 s16, v254, 4
	v_readlane_b32 s17, v254, 5
	v_readlane_b32 s18, v254, 6
	v_readlane_b32 s19, v254, 7
	s_mov_b64 s[44:45], exec
	s_branch .LBB0_823
